# DPP wave reductions + gemm_up row-rms loads issued together with counted vmcnt waits instead of one load per wait (bit-identical)
# speedup vs baseline: 1.0017x; 1.0017x over previous
; DEVI float bflo(unsigned w) { return __uint_as_float(w << 16); }
; DEVI float bfhi(unsigned w) { return __uint_as_float(w & 0xffff0000u); }
; DEVI void phase_gemm_up(const Params& p, int l, char* lds) {
;     ...
;     int tm, tn; tile_map(tile, NTM, NQ + NK, tm, tn);
;     const bool isq = tn < NQ;
;     const int m0 = tm * 256, n0 = (isq ? tn : tn - NQ) * 128;
;     const int K = isq ? 256 : 128;
;     const u16* A = feat + (long)m0 * NF + (isq ? F_MQ : F_MKV);
;     const u16* W = isq ? ((const u16*)(p.ws + OFF_WUQ) + (long)l * 1536 * 256 + (long)n0 * 256)
;                        : ((const u16*)(p.ws + OFF_WUKV) + (long)l * 2048 * 128 + (long)n0 * 128);
;     __syncthreads();
;     {
;       const int row = tid >> 1, half = tid & 1, n8 = K / 16;
;       const u16* ap = A + (long)row * NF + half * (K / 2);
;       float ss = 0.f;
;       for (int i = 0; i < n8; ++i) {
;         const u32x4 w = *(const u32x4*)(ap + i * 8);
; #pragma unroll
;         for (int j = 0; j < 4; ++j) { const float a = bflo(w[j]), b = bfhi(w[j]); ss += a * a + b * b; }
.LBB0_346:
	s_mul_hi_i32 s2, s17, 0x3e0f83e1
	s_lshr_b32 s3, s2, 31
	s_ashr_i32 s2, s2, 6
	s_add_i32 s2, s2, s3
	s_lshl_b32 s3, s2, 2
	s_mulk_i32 s2, 0xfef8
	s_add_i32 s2, s2, s17
	s_ashr_i32 s8, s2, 31
	s_lshr_b32 s8, s8, 30
	s_add_i32 s8, s2, s8
	s_add_i32 s2, s2, s3
	s_and_b32 s3, s8, -4
	s_ashr_i32 s10, s8, 2
	s_sub_i32 s12, s2, s3
	s_cmp_lt_i32 s12, 12
	s_cselect_b64 s[2:3], -1, 0
	s_lshl_b32 s26, s10, 8
	s_and_b64 s[8:9], s[2:3], exec
	s_mul_i32 s10, s10, 0x4c0000
	s_cselect_b32 s13, 0x100, s38
	s_mul_hi_i32 s8, s26, 0x4c00
	s_add_u32 s10, s44, s10
	s_addc_u32 s11, s45, s8
	s_and_b64 s[8:9], s[2:3], exec
	s_movk_i32 s8, 0x3000
	s_cselect_b32 s8, s8, 0x3200
	s_add_u32 s10, s10, s8
	s_addc_u32 s11, s11, 0
	s_and_b64 s[8:9], s[2:3], exec
	s_cselect_b32 s9, 7, 6
	v_lshlrev_b32_e32 v2, s9, v115
	v_lshl_add_u64 v[0:1], s[10:11], 0, v[112:113]
	v_lshlrev_b32_e32 v192, 1, v2
	s_lshr_b32 s8, s13, 4
	v_lshl_add_u64 v[0:1], v[0:1], 0, v[192:193]
	v_mov_b32_e32 v2, 0
	global_load_dwordx4 v[184:187], v[0:1], off
	global_load_dwordx4 v[188:191], v[0:1], off offset:16
	global_load_dwordx4 v[194:197], v[0:1], off offset:32
	global_load_dwordx4 v[198:201], v[0:1], off offset:48
	global_load_dwordx4 v[202:205], v[0:1], off offset:64
	global_load_dwordx4 v[216:219], v[0:1], off offset:80
	global_load_dwordx4 v[226:229], v[0:1], off offset:96
	global_load_dwordx4 v[230:233], v[0:1], off offset:112
	s_barrier
	s_cmp_eq_u32 s8, 16
	s_cbranch_scc0 .Lup_rms8
	global_load_dwordx4 v[234:237], v[0:1], off offset:128
	global_load_dwordx4 v[238:241], v[0:1], off offset:144
	global_load_dwordx4 v[242:245], v[0:1], off offset:160
	global_load_dwordx4 v[246:249], v[0:1], off offset:176
	s_waitcnt vmcnt(11)
	v_lshlrev_b32_e32 v8, 16, v184
	v_and_b32_e32 v9, 0xffff0000, v184
	v_pk_mul_f32 v[8:9], v[8:9], v[8:9]
	s_nop 0
	v_add_f32_e32 v3, v8, v9
	v_and_b32_e32 v9, 0xffff0000, v186
	v_and_b32_e32 v8, 0xffff0000, v185
	v_add_f32_e32 v10, v2, v3
	v_lshlrev_b32_e32 v3, 16, v186
	v_lshlrev_b32_e32 v2, 16, v185
	v_pk_mul_f32 v[184:185], v[8:9], v[8:9]
	s_nop 0
	v_pk_fma_f32 v[2:3], v[2:3], v[2:3], v[184:185]
	s_nop 0
	v_add_f32_e32 v2, v2, v10
	v_add_f32_e32 v184, v3, v2
	v_lshlrev_b32_e32 v2, 16, v187
	v_and_b32_e32 v3, 0xffff0000, v187
	v_pk_mul_f32 v[2:3], v[2:3], v[2:3]
	s_nop 0
	v_add_f32_e32 v2, v2, v3
	v_add_f32_e32 v2, v2, v184
	global_load_dwordx4 v[184:187], v[0:1], off offset:192
	s_waitcnt vmcnt(11)
	v_lshlrev_b32_e32 v8, 16, v188
	v_and_b32_e32 v9, 0xffff0000, v188
	v_pk_mul_f32 v[8:9], v[8:9], v[8:9]
	s_nop 0
	v_add_f32_e32 v3, v8, v9
	v_and_b32_e32 v9, 0xffff0000, v190
	v_and_b32_e32 v8, 0xffff0000, v189
	v_add_f32_e32 v10, v2, v3
	v_lshlrev_b32_e32 v3, 16, v190
	v_lshlrev_b32_e32 v2, 16, v189
	v_pk_mul_f32 v[188:189], v[8:9], v[8:9]
	s_nop 0
	v_pk_fma_f32 v[2:3], v[2:3], v[2:3], v[188:189]
	s_nop 0
	v_add_f32_e32 v2, v2, v10
	v_add_f32_e32 v188, v3, v2
	v_lshlrev_b32_e32 v2, 16, v191
	v_and_b32_e32 v3, 0xffff0000, v191
	v_pk_mul_f32 v[2:3], v[2:3], v[2:3]
	s_nop 0
	v_add_f32_e32 v2, v2, v3
	v_add_f32_e32 v2, v2, v188
	global_load_dwordx4 v[188:191], v[0:1], off offset:208
	s_waitcnt vmcnt(11)
	v_lshlrev_b32_e32 v8, 16, v194
	v_and_b32_e32 v9, 0xffff0000, v194
	v_pk_mul_f32 v[8:9], v[8:9], v[8:9]
	s_nop 0
	v_add_f32_e32 v3, v8, v9
	v_and_b32_e32 v9, 0xffff0000, v196
	v_and_b32_e32 v8, 0xffff0000, v195
	v_add_f32_e32 v10, v2, v3
	v_lshlrev_b32_e32 v3, 16, v196
	v_lshlrev_b32_e32 v2, 16, v195
	v_pk_mul_f32 v[194:195], v[8:9], v[8:9]
	s_nop 0
	v_pk_fma_f32 v[2:3], v[2:3], v[2:3], v[194:195]
	s_nop 0
	v_add_f32_e32 v2, v2, v10
	v_add_f32_e32 v194, v3, v2
	v_lshlrev_b32_e32 v2, 16, v197
	v_and_b32_e32 v3, 0xffff0000, v197
	v_pk_mul_f32 v[2:3], v[2:3], v[2:3]
	s_nop 0
	v_add_f32_e32 v2, v2, v3
	v_add_f32_e32 v2, v2, v194
	global_load_dwordx4 v[194:197], v[0:1], off offset:224
	s_waitcnt vmcnt(11)
	v_lshlrev_b32_e32 v8, 16, v198
	v_and_b32_e32 v9, 0xffff0000, v198
	v_pk_mul_f32 v[8:9], v[8:9], v[8:9]
	s_nop 0
	v_add_f32_e32 v3, v8, v9
	v_and_b32_e32 v9, 0xffff0000, v200
	v_and_b32_e32 v8, 0xffff0000, v199
	v_add_f32_e32 v10, v2, v3
	v_lshlrev_b32_e32 v3, 16, v200
	v_lshlrev_b32_e32 v2, 16, v199
	v_pk_mul_f32 v[198:199], v[8:9], v[8:9]
	s_nop 0
	v_pk_fma_f32 v[2:3], v[2:3], v[2:3], v[198:199]
	s_nop 0
	v_add_f32_e32 v2, v2, v10
	v_add_f32_e32 v198, v3, v2
	v_lshlrev_b32_e32 v2, 16, v201
	v_and_b32_e32 v3, 0xffff0000, v201
	v_pk_mul_f32 v[2:3], v[2:3], v[2:3]
	s_nop 0
	v_add_f32_e32 v2, v2, v3
	v_add_f32_e32 v2, v2, v198
	global_load_dwordx4 v[198:201], v[0:1], off offset:240
	s_waitcnt vmcnt(11)
	v_lshlrev_b32_e32 v8, 16, v202
	v_and_b32_e32 v9, 0xffff0000, v202
	v_pk_mul_f32 v[8:9], v[8:9], v[8:9]
	s_nop 0
	v_add_f32_e32 v3, v8, v9
	v_and_b32_e32 v9, 0xffff0000, v204
	v_and_b32_e32 v8, 0xffff0000, v203
	v_add_f32_e32 v10, v2, v3
	v_lshlrev_b32_e32 v3, 16, v204
	v_lshlrev_b32_e32 v2, 16, v203
	v_pk_mul_f32 v[202:203], v[8:9], v[8:9]
	s_nop 0
	v_pk_fma_f32 v[2:3], v[2:3], v[2:3], v[202:203]
	s_nop 0
	v_add_f32_e32 v2, v2, v10
	v_add_f32_e32 v202, v3, v2
	v_lshlrev_b32_e32 v2, 16, v205
	v_and_b32_e32 v3, 0xffff0000, v205
	v_pk_mul_f32 v[2:3], v[2:3], v[2:3]
	s_nop 0
	v_add_f32_e32 v2, v2, v3
	v_add_f32_e32 v2, v2, v202
	s_waitcnt vmcnt(10)
	v_lshlrev_b32_e32 v8, 16, v216
	v_and_b32_e32 v9, 0xffff0000, v216
	v_pk_mul_f32 v[8:9], v[8:9], v[8:9]
	s_nop 0
	v_add_f32_e32 v3, v8, v9
	v_and_b32_e32 v9, 0xffff0000, v218
	v_and_b32_e32 v8, 0xffff0000, v217
	v_add_f32_e32 v10, v2, v3
	v_lshlrev_b32_e32 v3, 16, v218
	v_lshlrev_b32_e32 v2, 16, v217
	v_pk_mul_f32 v[216:217], v[8:9], v[8:9]
	s_nop 0
	v_pk_fma_f32 v[2:3], v[2:3], v[2:3], v[216:217]
	s_nop 0
	v_add_f32_e32 v2, v2, v10
	v_add_f32_e32 v216, v3, v2
	v_lshlrev_b32_e32 v2, 16, v219
	v_and_b32_e32 v3, 0xffff0000, v219
	v_pk_mul_f32 v[2:3], v[2:3], v[2:3]
	s_nop 0
	v_add_f32_e32 v2, v2, v3
	v_add_f32_e32 v2, v2, v216
	s_waitcnt vmcnt(9)
; DEVI float bflo(unsigned w) { return __uint_as_float(w << 16); }
; DEVI float bfhi(unsigned w) { return __uint_as_float(w & 0xffff0000u); }
; DEVI void phase_gemm_up(const Params& p, int l, char* lds) {
;     ...
;       for (int i = 0; i < n8; ++i) {
;         const u32x4 w = *(const u32x4*)(ap + i * 8);
; #pragma unroll
;         for (int j = 0; j < 4; ++j) { const float a = bflo(w[j]), b = bfhi(w[j]); ss += a * a + b * b; }
	v_lshlrev_b32_e32 v8, 16, v226
	v_and_b32_e32 v9, 0xffff0000, v226
	v_pk_mul_f32 v[8:9], v[8:9], v[8:9]
	s_nop 0
	v_add_f32_e32 v3, v8, v9
	v_and_b32_e32 v9, 0xffff0000, v228
	v_and_b32_e32 v8, 0xffff0000, v227
	v_add_f32_e32 v10, v2, v3
	v_lshlrev_b32_e32 v3, 16, v228
	v_lshlrev_b32_e32 v2, 16, v227
	v_pk_mul_f32 v[226:227], v[8:9], v[8:9]
	s_nop 0
	v_pk_fma_f32 v[2:3], v[2:3], v[2:3], v[226:227]
	s_nop 0
	v_add_f32_e32 v2, v2, v10
	v_add_f32_e32 v226, v3, v2
	v_lshlrev_b32_e32 v2, 16, v229
	v_and_b32_e32 v3, 0xffff0000, v229
	v_pk_mul_f32 v[2:3], v[2:3], v[2:3]
	s_nop 0
	v_add_f32_e32 v2, v2, v3
	v_add_f32_e32 v2, v2, v226
	s_waitcnt vmcnt(8)
	v_lshlrev_b32_e32 v8, 16, v230
	v_and_b32_e32 v9, 0xffff0000, v230
	v_pk_mul_f32 v[8:9], v[8:9], v[8:9]
	s_nop 0
	v_add_f32_e32 v3, v8, v9
	v_and_b32_e32 v9, 0xffff0000, v232
	v_and_b32_e32 v8, 0xffff0000, v231
	v_add_f32_e32 v10, v2, v3
	v_lshlrev_b32_e32 v3, 16, v232
	v_lshlrev_b32_e32 v2, 16, v231
	v_pk_mul_f32 v[230:231], v[8:9], v[8:9]
	s_nop 0
	v_pk_fma_f32 v[2:3], v[2:3], v[2:3], v[230:231]
	s_nop 0
	v_add_f32_e32 v2, v2, v10
	v_add_f32_e32 v230, v3, v2
	v_lshlrev_b32_e32 v2, 16, v233
	v_and_b32_e32 v3, 0xffff0000, v233
	v_pk_mul_f32 v[2:3], v[2:3], v[2:3]
	s_nop 0
	v_add_f32_e32 v2, v2, v3
	v_add_f32_e32 v2, v2, v230
	s_waitcnt vmcnt(7)
	v_lshlrev_b32_e32 v8, 16, v234
	v_and_b32_e32 v9, 0xffff0000, v234
	v_pk_mul_f32 v[8:9], v[8:9], v[8:9]
	s_nop 0
	v_add_f32_e32 v3, v8, v9
	v_and_b32_e32 v9, 0xffff0000, v236
	v_and_b32_e32 v8, 0xffff0000, v235
	v_add_f32_e32 v10, v2, v3
	v_lshlrev_b32_e32 v3, 16, v236
	v_lshlrev_b32_e32 v2, 16, v235
	v_pk_mul_f32 v[234:235], v[8:9], v[8:9]
	s_nop 0
	v_pk_fma_f32 v[2:3], v[2:3], v[2:3], v[234:235]
	s_nop 0
	v_add_f32_e32 v2, v2, v10
	v_add_f32_e32 v234, v3, v2
	v_lshlrev_b32_e32 v2, 16, v237
	v_and_b32_e32 v3, 0xffff0000, v237
	v_pk_mul_f32 v[2:3], v[2:3], v[2:3]
	s_nop 0
	v_add_f32_e32 v2, v2, v3
	v_add_f32_e32 v2, v2, v234
	s_waitcnt vmcnt(6)
	v_lshlrev_b32_e32 v8, 16, v238
	v_and_b32_e32 v9, 0xffff0000, v238
	v_pk_mul_f32 v[8:9], v[8:9], v[8:9]
	s_nop 0
	v_add_f32_e32 v3, v8, v9
	v_and_b32_e32 v9, 0xffff0000, v240
	v_and_b32_e32 v8, 0xffff0000, v239
	v_add_f32_e32 v10, v2, v3
	v_lshlrev_b32_e32 v3, 16, v240
	v_lshlrev_b32_e32 v2, 16, v239
	v_pk_mul_f32 v[238:239], v[8:9], v[8:9]
	s_nop 0
	v_pk_fma_f32 v[2:3], v[2:3], v[2:3], v[238:239]
	s_nop 0
	v_add_f32_e32 v2, v2, v10
	v_add_f32_e32 v238, v3, v2
	v_lshlrev_b32_e32 v2, 16, v241
	v_and_b32_e32 v3, 0xffff0000, v241
	v_pk_mul_f32 v[2:3], v[2:3], v[2:3]
	s_nop 0
	v_add_f32_e32 v2, v2, v3
	v_add_f32_e32 v2, v2, v238
	s_waitcnt vmcnt(5)
	v_lshlrev_b32_e32 v8, 16, v242
	v_and_b32_e32 v9, 0xffff0000, v242
	v_pk_mul_f32 v[8:9], v[8:9], v[8:9]
	s_nop 0
	v_add_f32_e32 v3, v8, v9
	v_and_b32_e32 v9, 0xffff0000, v244
	v_and_b32_e32 v8, 0xffff0000, v243
	v_add_f32_e32 v10, v2, v3
	v_lshlrev_b32_e32 v3, 16, v244
	v_lshlrev_b32_e32 v2, 16, v243
	v_pk_mul_f32 v[242:243], v[8:9], v[8:9]
	s_nop 0
	v_pk_fma_f32 v[2:3], v[2:3], v[2:3], v[242:243]
	s_nop 0
	v_add_f32_e32 v2, v2, v10
	v_add_f32_e32 v242, v3, v2
	v_lshlrev_b32_e32 v2, 16, v245
	v_and_b32_e32 v3, 0xffff0000, v245
	v_pk_mul_f32 v[2:3], v[2:3], v[2:3]
	s_nop 0
	v_add_f32_e32 v2, v2, v3
	v_add_f32_e32 v2, v2, v242
	s_waitcnt vmcnt(4)
	v_lshlrev_b32_e32 v8, 16, v246
	v_and_b32_e32 v9, 0xffff0000, v246
	v_pk_mul_f32 v[8:9], v[8:9], v[8:9]
	s_nop 0
	v_add_f32_e32 v3, v8, v9
	v_and_b32_e32 v9, 0xffff0000, v248
	v_and_b32_e32 v8, 0xffff0000, v247
	v_add_f32_e32 v10, v2, v3
	v_lshlrev_b32_e32 v3, 16, v248
	v_lshlrev_b32_e32 v2, 16, v247
	v_pk_mul_f32 v[246:247], v[8:9], v[8:9]
	s_nop 0
	v_pk_fma_f32 v[2:3], v[2:3], v[2:3], v[246:247]
	s_nop 0
	v_add_f32_e32 v2, v2, v10
	v_add_f32_e32 v246, v3, v2
	v_lshlrev_b32_e32 v2, 16, v249
	v_and_b32_e32 v3, 0xffff0000, v249
	v_pk_mul_f32 v[2:3], v[2:3], v[2:3]
	s_nop 0
	v_add_f32_e32 v2, v2, v3
	v_add_f32_e32 v2, v2, v246
	s_waitcnt vmcnt(3)
	v_lshlrev_b32_e32 v8, 16, v184
	v_and_b32_e32 v9, 0xffff0000, v184
	v_pk_mul_f32 v[8:9], v[8:9], v[8:9]
	s_nop 0
	v_add_f32_e32 v3, v8, v9
	v_and_b32_e32 v9, 0xffff0000, v186
	v_and_b32_e32 v8, 0xffff0000, v185
	v_add_f32_e32 v10, v2, v3
	v_lshlrev_b32_e32 v3, 16, v186
	v_lshlrev_b32_e32 v2, 16, v185
	v_pk_mul_f32 v[184:185], v[8:9], v[8:9]
	s_nop 0
	v_pk_fma_f32 v[2:3], v[2:3], v[2:3], v[184:185]
	s_nop 0
	v_add_f32_e32 v2, v2, v10
	v_add_f32_e32 v184, v3, v2
	v_lshlrev_b32_e32 v2, 16, v187
	v_and_b32_e32 v3, 0xffff0000, v187
	v_pk_mul_f32 v[2:3], v[2:3], v[2:3]
	s_nop 0
	v_add_f32_e32 v2, v2, v3
	v_add_f32_e32 v2, v2, v184
	s_waitcnt vmcnt(2)
	v_lshlrev_b32_e32 v8, 16, v188
	v_and_b32_e32 v9, 0xffff0000, v188
	v_pk_mul_f32 v[8:9], v[8:9], v[8:9]
	s_nop 0
	v_add_f32_e32 v3, v8, v9
	v_and_b32_e32 v9, 0xffff0000, v190
	v_and_b32_e32 v8, 0xffff0000, v189
	v_add_f32_e32 v10, v2, v3
	v_lshlrev_b32_e32 v3, 16, v190
	v_lshlrev_b32_e32 v2, 16, v189
	v_pk_mul_f32 v[188:189], v[8:9], v[8:9]
	s_nop 0
	v_pk_fma_f32 v[2:3], v[2:3], v[2:3], v[188:189]
	s_nop 0
	v_add_f32_e32 v2, v2, v10
	v_add_f32_e32 v188, v3, v2
	v_lshlrev_b32_e32 v2, 16, v191
	v_and_b32_e32 v3, 0xffff0000, v191
	v_pk_mul_f32 v[2:3], v[2:3], v[2:3]
	s_nop 0
	v_add_f32_e32 v2, v2, v3
	v_add_f32_e32 v2, v2, v188
	s_waitcnt vmcnt(1)
	v_lshlrev_b32_e32 v8, 16, v194
	v_and_b32_e32 v9, 0xffff0000, v194
	v_pk_mul_f32 v[8:9], v[8:9], v[8:9]
	s_nop 0
	v_add_f32_e32 v3, v8, v9
	v_and_b32_e32 v9, 0xffff0000, v196
	v_and_b32_e32 v8, 0xffff0000, v195
	v_add_f32_e32 v10, v2, v3
	v_lshlrev_b32_e32 v3, 16, v196
	v_lshlrev_b32_e32 v2, 16, v195
	v_pk_mul_f32 v[194:195], v[8:9], v[8:9]
	s_nop 0
	v_pk_fma_f32 v[2:3], v[2:3], v[2:3], v[194:195]
	s_nop 0
	v_add_f32_e32 v2, v2, v10
	v_add_f32_e32 v194, v3, v2
	v_lshlrev_b32_e32 v2, 16, v197
	v_and_b32_e32 v3, 0xffff0000, v197
	v_pk_mul_f32 v[2:3], v[2:3], v[2:3]
	s_nop 0
	v_add_f32_e32 v2, v2, v3
	v_add_f32_e32 v2, v2, v194
	s_waitcnt vmcnt(0)
	v_lshlrev_b32_e32 v8, 16, v198
	v_and_b32_e32 v9, 0xffff0000, v198
	v_pk_mul_f32 v[8:9], v[8:9], v[8:9]
	s_nop 0
	v_add_f32_e32 v3, v8, v9
	v_and_b32_e32 v9, 0xffff0000, v200
	v_and_b32_e32 v8, 0xffff0000, v199
	v_add_f32_e32 v10, v2, v3
	v_lshlrev_b32_e32 v3, 16, v200
	v_lshlrev_b32_e32 v2, 16, v199
	v_pk_mul_f32 v[198:199], v[8:9], v[8:9]
	s_nop 0
	v_pk_fma_f32 v[2:3], v[2:3], v[2:3], v[198:199]
	s_nop 0
	v_add_f32_e32 v2, v2, v10
	v_add_f32_e32 v198, v3, v2
	v_lshlrev_b32_e32 v2, 16, v201
	v_and_b32_e32 v3, 0xffff0000, v201
	v_pk_mul_f32 v[2:3], v[2:3], v[2:3]
	s_nop 0
	v_add_f32_e32 v2, v2, v3
	v_add_f32_e32 v2, v2, v198
	s_branch .Lup_rms_done
; DEVI float bflo(unsigned w) { return __uint_as_float(w << 16); }
; DEVI float bfhi(unsigned w) { return __uint_as_float(w & 0xffff0000u); }
; DEVI void phase_gemm_up(const Params& p, int l, char* lds) {
;     ...
;       for (int i = 0; i < n8; ++i) {
;         const u32x4 w = *(const u32x4*)(ap + i * 8);
; #pragma unroll
;         for (int j = 0; j < 4; ++j) { const float a = bflo(w[j]), b = bfhi(w[j]); ss += a * a + b * b; }
;       }
;       ss += __shfl_xor(ss, 1);
;       if (half == 0) rs[row] = rsqrtf(ss / (float)K + EPS);
.Lup_rms8:
	s_waitcnt vmcnt(7)
	v_lshlrev_b32_e32 v8, 16, v184
	v_and_b32_e32 v9, 0xffff0000, v184
	v_pk_mul_f32 v[8:9], v[8:9], v[8:9]
	s_nop 0
	v_add_f32_e32 v3, v8, v9
	v_and_b32_e32 v9, 0xffff0000, v186
	v_and_b32_e32 v8, 0xffff0000, v185
	v_add_f32_e32 v10, v2, v3
	v_lshlrev_b32_e32 v3, 16, v186
	v_lshlrev_b32_e32 v2, 16, v185
	v_pk_mul_f32 v[184:185], v[8:9], v[8:9]
	s_nop 0
	v_pk_fma_f32 v[2:3], v[2:3], v[2:3], v[184:185]
	s_nop 0
	v_add_f32_e32 v2, v2, v10
	v_add_f32_e32 v184, v3, v2
	v_lshlrev_b32_e32 v2, 16, v187
	v_and_b32_e32 v3, 0xffff0000, v187
	v_pk_mul_f32 v[2:3], v[2:3], v[2:3]
	s_nop 0
	v_add_f32_e32 v2, v2, v3
	v_add_f32_e32 v2, v2, v184
	s_waitcnt vmcnt(6)
	v_lshlrev_b32_e32 v8, 16, v188
	v_and_b32_e32 v9, 0xffff0000, v188
	v_pk_mul_f32 v[8:9], v[8:9], v[8:9]
	s_nop 0
	v_add_f32_e32 v3, v8, v9
	v_and_b32_e32 v9, 0xffff0000, v190
	v_and_b32_e32 v8, 0xffff0000, v189
	v_add_f32_e32 v10, v2, v3
	v_lshlrev_b32_e32 v3, 16, v190
	v_lshlrev_b32_e32 v2, 16, v189
	v_pk_mul_f32 v[188:189], v[8:9], v[8:9]
	s_nop 0
	v_pk_fma_f32 v[2:3], v[2:3], v[2:3], v[188:189]
	s_nop 0
	v_add_f32_e32 v2, v2, v10
	v_add_f32_e32 v188, v3, v2
	v_lshlrev_b32_e32 v2, 16, v191
	v_and_b32_e32 v3, 0xffff0000, v191
	v_pk_mul_f32 v[2:3], v[2:3], v[2:3]
	s_nop 0
	v_add_f32_e32 v2, v2, v3
	v_add_f32_e32 v2, v2, v188
	s_waitcnt vmcnt(5)
	v_lshlrev_b32_e32 v8, 16, v194
	v_and_b32_e32 v9, 0xffff0000, v194
	v_pk_mul_f32 v[8:9], v[8:9], v[8:9]
	s_nop 0
	v_add_f32_e32 v3, v8, v9
	v_and_b32_e32 v9, 0xffff0000, v196
	v_and_b32_e32 v8, 0xffff0000, v195
	v_add_f32_e32 v10, v2, v3
	v_lshlrev_b32_e32 v3, 16, v196
	v_lshlrev_b32_e32 v2, 16, v195
	v_pk_mul_f32 v[194:195], v[8:9], v[8:9]
	s_nop 0
	v_pk_fma_f32 v[2:3], v[2:3], v[2:3], v[194:195]
	s_nop 0
	v_add_f32_e32 v2, v2, v10
	v_add_f32_e32 v194, v3, v2
	v_lshlrev_b32_e32 v2, 16, v197
	v_and_b32_e32 v3, 0xffff0000, v197
	v_pk_mul_f32 v[2:3], v[2:3], v[2:3]
	s_nop 0
	v_add_f32_e32 v2, v2, v3
	v_add_f32_e32 v2, v2, v194
	s_waitcnt vmcnt(4)
	v_lshlrev_b32_e32 v8, 16, v198
	v_and_b32_e32 v9, 0xffff0000, v198
	v_pk_mul_f32 v[8:9], v[8:9], v[8:9]
	s_nop 0
	v_add_f32_e32 v3, v8, v9
	v_and_b32_e32 v9, 0xffff0000, v200
	v_and_b32_e32 v8, 0xffff0000, v199
	v_add_f32_e32 v10, v2, v3
	v_lshlrev_b32_e32 v3, 16, v200
	v_lshlrev_b32_e32 v2, 16, v199
	v_pk_mul_f32 v[198:199], v[8:9], v[8:9]
	s_nop 0
	v_pk_fma_f32 v[2:3], v[2:3], v[2:3], v[198:199]
	s_nop 0
	v_add_f32_e32 v2, v2, v10
	v_add_f32_e32 v198, v3, v2
	v_lshlrev_b32_e32 v2, 16, v201
	v_and_b32_e32 v3, 0xffff0000, v201
	v_pk_mul_f32 v[2:3], v[2:3], v[2:3]
	s_nop 0
	v_add_f32_e32 v2, v2, v3
	v_add_f32_e32 v2, v2, v198
	s_waitcnt vmcnt(3)
	v_lshlrev_b32_e32 v8, 16, v202
	v_and_b32_e32 v9, 0xffff0000, v202
	v_pk_mul_f32 v[8:9], v[8:9], v[8:9]
	s_nop 0
	v_add_f32_e32 v3, v8, v9
	v_and_b32_e32 v9, 0xffff0000, v204
	v_and_b32_e32 v8, 0xffff0000, v203
	v_add_f32_e32 v10, v2, v3
	v_lshlrev_b32_e32 v3, 16, v204
	v_lshlrev_b32_e32 v2, 16, v203
	v_pk_mul_f32 v[202:203], v[8:9], v[8:9]
	s_nop 0
	v_pk_fma_f32 v[2:3], v[2:3], v[2:3], v[202:203]
	s_nop 0
	v_add_f32_e32 v2, v2, v10
	v_add_f32_e32 v202, v3, v2
	v_lshlrev_b32_e32 v2, 16, v205
	v_and_b32_e32 v3, 0xffff0000, v205
	v_pk_mul_f32 v[2:3], v[2:3], v[2:3]
	s_nop 0
	v_add_f32_e32 v2, v2, v3
	v_add_f32_e32 v2, v2, v202
	s_waitcnt vmcnt(2)
	v_lshlrev_b32_e32 v8, 16, v216
	v_and_b32_e32 v9, 0xffff0000, v216
	v_pk_mul_f32 v[8:9], v[8:9], v[8:9]
	s_nop 0
	v_add_f32_e32 v3, v8, v9
	v_and_b32_e32 v9, 0xffff0000, v218
	v_and_b32_e32 v8, 0xffff0000, v217
	v_add_f32_e32 v10, v2, v3
	v_lshlrev_b32_e32 v3, 16, v218
	v_lshlrev_b32_e32 v2, 16, v217
	v_pk_mul_f32 v[216:217], v[8:9], v[8:9]
	s_nop 0
	v_pk_fma_f32 v[2:3], v[2:3], v[2:3], v[216:217]
	s_nop 0
	v_add_f32_e32 v2, v2, v10
	v_add_f32_e32 v216, v3, v2
	v_lshlrev_b32_e32 v2, 16, v219
	v_and_b32_e32 v3, 0xffff0000, v219
	v_pk_mul_f32 v[2:3], v[2:3], v[2:3]
	s_nop 0
	v_add_f32_e32 v2, v2, v3
	v_add_f32_e32 v2, v2, v216
	s_waitcnt vmcnt(1)
	v_lshlrev_b32_e32 v8, 16, v226
	v_and_b32_e32 v9, 0xffff0000, v226
	v_pk_mul_f32 v[8:9], v[8:9], v[8:9]
	s_nop 0
	v_add_f32_e32 v3, v8, v9
	v_and_b32_e32 v9, 0xffff0000, v228
	v_and_b32_e32 v8, 0xffff0000, v227
	v_add_f32_e32 v10, v2, v3
	v_lshlrev_b32_e32 v3, 16, v228
	v_lshlrev_b32_e32 v2, 16, v227
	v_pk_mul_f32 v[226:227], v[8:9], v[8:9]
	s_nop 0
	v_pk_fma_f32 v[2:3], v[2:3], v[2:3], v[226:227]
	s_nop 0
	v_add_f32_e32 v2, v2, v10
	v_add_f32_e32 v226, v3, v2
	v_lshlrev_b32_e32 v2, 16, v229
	v_and_b32_e32 v3, 0xffff0000, v229
	v_pk_mul_f32 v[2:3], v[2:3], v[2:3]
	s_nop 0
	v_add_f32_e32 v2, v2, v3
	v_add_f32_e32 v2, v2, v226
	s_waitcnt vmcnt(0)
	v_lshlrev_b32_e32 v8, 16, v230
	v_and_b32_e32 v9, 0xffff0000, v230
	v_pk_mul_f32 v[8:9], v[8:9], v[8:9]
	s_nop 0
	v_add_f32_e32 v3, v8, v9
	v_and_b32_e32 v9, 0xffff0000, v232
	v_and_b32_e32 v8, 0xffff0000, v231
	v_add_f32_e32 v10, v2, v3
	v_lshlrev_b32_e32 v3, 16, v232
	v_lshlrev_b32_e32 v2, 16, v231
	v_pk_mul_f32 v[230:231], v[8:9], v[8:9]
	s_nop 0
	v_pk_fma_f32 v[2:3], v[2:3], v[2:3], v[230:231]
	s_nop 0
	v_add_f32_e32 v2, v2, v10
	v_add_f32_e32 v230, v3, v2
	v_lshlrev_b32_e32 v2, 16, v233
	v_and_b32_e32 v3, 0xffff0000, v233
	v_pk_mul_f32 v[2:3], v[2:3], v[2:3]
	s_nop 0
	v_add_f32_e32 v2, v2, v3
	v_add_f32_e32 v2, v2, v230
.Lup_rms_done:
	ds_bpermute_b32 v0, v130, v2
	s_and_saveexec_b64 s[8:9], s[6:7]
	s_cbranch_execz .LBB0_350
	v_cvt_f32_u32_e32 v1, s13
	s_waitcnt lgkmcnt(0)
	v_add_f32_e32 v0, v2, v0
	v_div_scale_f32 v2, s[14:15], v1, v1, v0
	v_rcp_f32_e32 v3, v2
	v_div_scale_f32 v4, vcc, v0, v1, v0
	v_fma_f32 v5, -v2, v3, 1.0
	v_fmac_f32_e32 v3, v5, v3
	v_mul_f32_e32 v5, v4, v3
	v_fma_f32 v6, -v2, v5, v4
	v_fmac_f32_e32 v5, v6, v3
	v_fma_f32 v2, -v2, v5, v4
	v_div_fmas_f32 v2, v2, v3, v5
	v_div_fixup_f32 v0, v2, v1, v0
	v_add_f32_e32 v0, 0x358637bd, v0
	v_mul_f32_e32 v1, 0x4b800000, v0
	v_cmp_gt_f32_e32 vcc, s59, v0
	s_nop 1
	v_cndmask_b32_e32 v0, v0, v1, vcc
	v_rsq_f32_e32 v0, v0
	s_nop 0
	v_mul_f32_e32 v1, 0x45800000, v0
	v_cndmask_b32_e32 v0, v0, v1, vcc
	ds_write_b32 v131, v0
